# GEMM1 epilogue: Y stores use SGPR base + 32-bit offset (64-bit VALU address ops and dead r0 address adds removed)
# baseline (speedup 1.0000x reference)
.LBB0_442:
	s_lshl_b32 s55, s52, 8
	v_add_u32_e32 v184, s55, v165
	v_mbcnt_lo_u32_b32 v128, -1, 0
	v_mbcnt_hi_u32_b32 v128, -1, v128
	v_add_u32_e32 v158, 0xb0, v184
	v_add_u32_e32 v170, 0x80, v184
	v_add_u32_e32 v162, 0x90, v184
	v_add_u32_e32 v160, 0xa0, v184
	s_waitcnt vmcnt(14)
	v_mov_b32_e32 v178, v245
	v_mov_b32_e32 v168, v250
	v_mov_b32_e32 v186, v242
	v_mov_b32_e32 v182, v243
	v_mov_b32_e32 v180, v244
	v_mov_b32_e32 v176, v246
	v_mov_b32_e32 v164, v248
	v_mov_b32_e32 v166, v249
	v_pk_mul_f32 v[108:109], v[108:109], v[178:179] op_sel_hi:[1,0]
	v_pk_mul_f32 v[110:111], v[110:111], v[178:179] op_sel_hi:[1,0]
	v_pk_mul_f32 v[104:105], v[104:105], v[178:179] op_sel_hi:[1,0]
	v_pk_mul_f32 v[106:107], v[106:107], v[178:179] op_sel_hi:[1,0]
	v_pk_mul_f32 v[128:129], v[108:109], v[104:105]
	v_pk_mul_f32 v[130:131], v[110:111], v[106:107]
	v_pk_mul_f32 v[100:101], v[100:101], v[168:169] op_sel_hi:[1,0]
	v_pk_mul_f32 v[102:103], v[102:103], v[168:169] op_sel_hi:[1,0]
	v_pk_mul_f32 v[92:93], v[92:93], v[168:169] op_sel_hi:[1,0]
	v_pk_mul_f32 v[94:95], v[94:95], v[168:169] op_sel_hi:[1,0]
	v_pk_mul_f32 v[92:93], v[100:101], v[92:93]
	v_pk_mul_f32 v[94:95], v[102:103], v[94:95]
	s_and_saveexec_b64 s[64:65], s[4:5]
	s_cbranch_execz .LBB0_444
	ds_write_b128 v195, v[128:131]
	ds_write_b128 v195, v[92:95] offset:1024

.LBB0_449:
	v_pk_mul_f32 v[112:113], v[112:113], v[186:187] op_sel_hi:[1,0]
	v_pk_mul_f32 v[114:115], v[114:115], v[186:187] op_sel_hi:[1,0]
	v_mul_f32_e32 v169, 0xbfb8aa3b, v112
	v_exp_f32_e32 v169, v169
	v_mul_f32_e32 v179, 0xbfb8aa3b, v114
	v_pk_mul_f32 v[126:127], v[126:127], v[186:187] op_sel_hi:[1,0]
	v_pk_mul_f32 v[124:125], v[124:125], v[186:187] op_sel_hi:[1,0]
	v_add_f32_e32 v169, 1.0, v169
	v_pk_mul_f32 v[122:123], v[122:123], v[186:187] op_sel_hi:[1,0]
	v_pk_mul_f32 v[120:121], v[120:121], v[186:187] op_sel_hi:[1,0]
	v_pk_mul_f32 v[118:119], v[118:119], v[186:187] op_sel_hi:[1,0]
	v_pk_mul_f32 v[116:117], v[116:117], v[186:187] op_sel_hi:[1,0]
	v_rcp_f32_e32 v196, v169
	v_mul_f32_e32 v169, 0xbfb8aa3b, v113
	v_exp_f32_e32 v179, v179
	v_mul_f32_e32 v186, 0xbfb8aa3b, v115
	v_exp_f32_e32 v169, v169
	v_exp_f32_e32 v186, v186
	v_add_f32_e32 v179, 1.0, v179
	v_rcp_f32_e32 v198, v179
	v_add_f32_e32 v169, 1.0, v169
	v_add_f32_e32 v179, 1.0, v186
	v_rcp_f32_e32 v199, v179
	v_rcp_f32_e32 v197, v169
	v_pk_mul_f32 v[118:119], v[122:123], v[118:119]
	v_pk_mul_f32 v[116:117], v[120:121], v[116:117]
	v_pk_mul_f32 v[114:115], v[114:115], v[198:199]
	v_pk_mul_f32 v[112:113], v[112:113], v[196:197]
	v_pk_mul_f32 v[114:115], v[126:127], v[114:115]
	v_pk_mul_f32 v[112:113], v[124:125], v[112:113]
	s_waitcnt lgkmcnt(0)
	v_cndmask_b32_e64 v138, v134, v138, s[6:7]
	v_cndmask_b32_e64 v139, v135, v139, s[6:7]
	v_mov_b32_dpp v125, v118 row_ror:2 row_mask:0xf bank_mask:0xf
	v_mov_b32_dpp v127, v119 row_ror:2 row_mask:0xf bank_mask:0xf
	v_cndmask_b32_e64 v136, v132, v136, s[6:7]
	v_cndmask_b32_e64 v137, v133, v137, s[6:7]
	v_mov_b32_dpp v121, v116 row_ror:2 row_mask:0xf bank_mask:0xf
	v_mov_b32_dpp v123, v117 row_ror:2 row_mask:0xf bank_mask:0xf
	v_mov_b32_dpp v124, v118 row_ror:1 row_mask:0xf bank_mask:0xf
	v_mov_b32_dpp v126, v119 row_ror:1 row_mask:0xf bank_mask:0xf
	v_cndmask_b32_e64 v138, v138, v125, s[8:9]
	v_cndmask_b32_e64 v139, v139, v127, s[8:9]
	v_mov_b32_dpp v120, v116 row_ror:1 row_mask:0xf bank_mask:0xf
	v_mov_b32_dpp v122, v117 row_ror:1 row_mask:0xf bank_mask:0xf
	v_cndmask_b32_e64 v136, v136, v121, s[8:9]
	v_cndmask_b32_e64 v137, v137, v123, s[8:9]
	v_cndmask_b32_e64 v134, v124, v134, s[6:7]
	v_cndmask_b32_e64 v135, v126, v135, s[6:7]
	v_pk_mul_f32 v[138:139], v[110:111], v[138:139]
	v_cndmask_b32_e64 v132, v120, v132, s[6:7]
	v_cndmask_b32_e64 v133, v122, v133, s[6:7]
	v_pk_mul_f32 v[136:137], v[108:109], v[136:137]
	v_pk_fma_f32 v[134:135], v[106:107], v[134:135], v[138:139]
	v_pk_fma_f32 v[132:133], v[104:105], v[132:133], v[136:137]
	v_pk_fma_f32 v[118:119], v[118:119], v[102:103], v[134:135]
	v_lshlrev_b32_e32 v134, 11, v184
	v_pk_fma_f32 v[116:117], v[116:117], v[100:101], v[132:133]
	v_pk_mul_f32 v[118:119], v[114:115], v[118:119]
	v_pk_mul_f32 v[116:117], v[112:113], v[116:117]
	v_lshl_add_u32 v134, v172, 1, v134
	v_cvt_pk_bf16_f32 v132, v116, v117
	v_cvt_pk_bf16_f32 v133, v118, v119
	global_store_dwordx2 v134, v[132:133], s[18:19]
	s_and_saveexec_b64 s[62:63], s[46:47]
	s_cbranch_execz .LBB0_451
	s_ashr_i32 s53, s52, 31
	s_lshl_b64 s[64:65], s[52:53], 13
	v_lshl_add_u64 v[132:133], v[146:147], 0, s[64:65]
	v_lshl_add_u64 v[132:133], v[132:133], 0, v[174:175]
	global_store_dwordx4 v[132:133], v[112:115], off
	v_lshl_add_u64 v[132:133], v[148:149], 0, s[64:65]
	v_lshl_add_u64 v[132:133], v[132:133], 0, v[174:175]
	global_store_dwordx4 v[132:133], v[116:119], off
.LBB0_451:
	s_or_b64 exec, exec, s[62:63]
	v_pk_mul_f32 v[88:89], v[88:89], v[182:183] op_sel_hi:[1,0]
	v_pk_mul_f32 v[84:85], v[84:85], v[182:183] op_sel_hi:[1,0]
	v_pk_mul_f32 v[64:65], v[64:65], v[180:181] op_sel_hi:[1,0]
	v_pk_mul_f32 v[84:85], v[88:89], v[84:85]
	v_mul_f32_e32 v88, 0xbfb8aa3b, v64
	v_mul_f32_e32 v89, 0xbfb8aa3b, v65
	v_exp_f32_e32 v88, v88
	v_exp_f32_e32 v89, v89
	v_mov_b32_e32 v179, v178
	v_pk_mul_f32 v[76:77], v[76:77], v[180:181] op_sel_hi:[1,0]
	v_add_f32_e32 v88, 1.0, v88
	v_add_f32_e32 v89, 1.0, v89
	v_rcp_f32_e32 v88, v88
	v_rcp_f32_e32 v89, v89
	v_pk_mul_f32 v[72:73], v[72:73], v[180:181] op_sel_hi:[1,0]
	v_pk_mul_f32 v[68:69], v[68:69], v[180:181] op_sel_hi:[1,0]
	v_pk_mul_f32 v[56:57], v[56:57], v[178:179]
	v_pk_mul_f32 v[64:65], v[64:65], v[88:89]
	v_pk_mul_f32 v[74:75], v[74:75], v[180:181] op_sel_hi:[1,0]
	v_pk_mul_f32 v[70:71], v[70:71], v[180:181] op_sel_hi:[1,0]
	v_pk_mul_f32 v[68:69], v[72:73], v[68:69]
	v_pk_mul_f32 v[72:73], v[76:77], v[64:65]
	v_mul_f32_e32 v64, 0xbfb8aa3b, v56
	v_pk_mul_f32 v[90:91], v[90:91], v[182:183] op_sel_hi:[1,0]
	v_pk_mul_f32 v[86:87], v[86:87], v[182:183] op_sel_hi:[1,0]
	v_pk_mul_f32 v[66:67], v[66:67], v[180:181] op_sel_hi:[1,0]
	v_pk_mul_f32 v[70:71], v[74:75], v[70:71]
	v_exp_f32_e32 v74, v64
	v_mov_b32_e32 v64, v178
	v_mov_b32_e32 v65, v178
	v_pk_mul_f32 v[86:87], v[90:91], v[86:87]
	v_mul_f32_e32 v90, 0xbfb8aa3b, v66
	v_mul_f32_e32 v91, 0xbfb8aa3b, v67
	v_pk_mul_f32 v[58:59], v[58:59], v[64:65]
	v_exp_f32_e32 v90, v90
	v_exp_f32_e32 v91, v91
	v_mul_f32_e32 v76, 0xbfb8aa3b, v58
	v_mul_f32_e32 v77, 0xbfb8aa3b, v59
	v_exp_f32_e32 v76, v76
	v_exp_f32_e32 v77, v77
	v_mul_f32_e32 v75, 0xbfb8aa3b, v57
	v_pk_mul_f32 v[80:81], v[80:81], v[182:183] op_sel_hi:[1,0]
	v_pk_mul_f32 v[82:83], v[82:83], v[182:183] op_sel_hi:[1,0]
	v_exp_f32_e32 v75, v75
	v_mul_f32_e32 v116, 0xbfb8aa3b, v80
	v_mul_f32_e32 v117, 0xbfb8aa3b, v81
	v_mul_f32_e32 v118, 0xbfb8aa3b, v82
	v_mul_f32_e32 v119, 0xbfb8aa3b, v83
	v_add_f32_e32 v90, 1.0, v90
	v_add_f32_e32 v91, 1.0, v91
	v_exp_f32_e32 v116, v116
	v_exp_f32_e32 v117, v117
	v_exp_f32_e32 v118, v118
	v_exp_f32_e32 v119, v119
	v_rcp_f32_e32 v90, v90
	v_rcp_f32_e32 v91, v91
	v_add_f32_e32 v76, 1.0, v76
	v_add_f32_e32 v77, 1.0, v77
	v_rcp_f32_e32 v76, v76
	v_rcp_f32_e32 v77, v77
	v_add_f32_e32 v74, 1.0, v74
	v_add_f32_e32 v75, 1.0, v75
	v_rcp_f32_e32 v74, v74
	v_rcp_f32_e32 v75, v75
	v_add_f32_e32 v116, 1.0, v116
	v_add_f32_e32 v117, 1.0, v117
	v_add_f32_e32 v118, 1.0, v118
	v_add_f32_e32 v119, 1.0, v119
	v_pk_mul_f32 v[78:79], v[78:79], v[180:181] op_sel_hi:[1,0]
	v_pk_mul_f32 v[66:67], v[66:67], v[90:91]
	v_rcp_f32_e32 v116, v116
	v_rcp_f32_e32 v118, v118
	v_rcp_f32_e32 v119, v119
	v_rcp_f32_e32 v117, v117
	v_pk_mul_f32 v[66:67], v[78:79], v[66:67]
	v_pk_mul_f32 v[58:59], v[58:59], v[76:77]
	v_pk_mul_f32 v[62:63], v[62:63], v[64:65]
	v_mov_b32_dpp v77, v84 row_ror:2 row_mask:0xf bank_mask:0xf
	v_mov_b32_dpp v79, v85 row_ror:2 row_mask:0xf bank_mask:0xf
	v_mov_b32_dpp v89, v86 row_ror:2 row_mask:0xf bank_mask:0xf
	v_mov_b32_dpp v91, v87 row_ror:2 row_mask:0xf bank_mask:0xf
	v_pk_mul_f32 v[60:61], v[60:61], v[178:179]
	v_pk_mul_f32 v[56:57], v[56:57], v[74:75]
	v_pk_mul_f32 v[58:59], v[62:63], v[58:59]
	v_mov_b32_dpp v76, v84 row_ror:1 row_mask:0xf bank_mask:0xf
	v_mov_b32_dpp v78, v85 row_ror:1 row_mask:0xf bank_mask:0xf
	v_mov_b32_dpp v88, v86 row_ror:1 row_mask:0xf bank_mask:0xf
	v_mov_b32_dpp v90, v87 row_ror:1 row_mask:0xf bank_mask:0xf
	v_cndmask_b32_e64 v62, v121, v77, s[8:9]
	v_cndmask_b32_e64 v63, v123, v79, s[8:9]
	v_cndmask_b32_e64 v74, v125, v89, s[8:9]
	v_cndmask_b32_e64 v75, v127, v91, s[8:9]
	v_pk_mul_f32 v[56:57], v[60:61], v[56:57]
	v_cndmask_b32_e64 v60, v76, v120, s[6:7]
	v_cndmask_b32_e64 v61, v78, v122, s[6:7]
	v_cndmask_b32_e64 v64, v88, v124, s[6:7]
	v_cndmask_b32_e64 v65, v90, v126, s[6:7]
	v_pk_mul_f32 v[74:75], v[110:111], v[74:75]
	v_pk_mul_f32 v[62:63], v[108:109], v[62:63]
	v_pk_mul_f32 v[98:99], v[98:99], v[182:183] op_sel_hi:[1,0]
	v_pk_mul_f32 v[96:97], v[96:97], v[182:183] op_sel_hi:[1,0]
	v_pk_mul_f32 v[82:83], v[82:83], v[118:119]
	v_pk_mul_f32 v[80:81], v[80:81], v[116:117]
	v_pk_fma_f32 v[64:65], v[106:107], v[64:65], v[74:75]
	v_pk_fma_f32 v[60:61], v[104:105], v[60:61], v[62:63]
	v_pk_mul_f32 v[82:83], v[98:99], v[82:83]
	v_pk_mul_f32 v[80:81], v[96:97], v[80:81]
	v_pk_fma_f32 v[62:63], v[86:87], v[102:103], v[64:65]
	v_pk_fma_f32 v[60:61], v[84:85], v[100:101], v[60:61]
	v_add_u32_e32 v64, s55, v181
	v_pk_mul_f32 v[62:63], v[82:83], v[62:63]
	v_pk_mul_f32 v[60:61], v[80:81], v[60:61]
	v_cvt_pk_bf16_f32 v60, v60, v61
	v_cvt_pk_bf16_f32 v61, v62, v63
	v_lshlrev_b32_e32 v62, 11, v64
	v_lshlrev_b32_e32 v64, 1, v172
	v_add_u32_e32 v62, v62, v64
	v_mov_b32_dpp v80, v68 row_ror:1 row_mask:0xf bank_mask:0xf
	v_mov_b32_dpp v81, v68 row_ror:2 row_mask:0xf bank_mask:0xf
	v_mov_b32_dpp v85, v70 row_ror:2 row_mask:0xf bank_mask:0xf
	v_mov_b32_dpp v87, v71 row_ror:2 row_mask:0xf bank_mask:0xf
	global_store_dwordx2 v62, v[60:61], s[18:19]
	v_mov_b32_dpp v83, v69 row_ror:2 row_mask:0xf bank_mask:0xf
	v_mov_b32_dpp v84, v70 row_ror:1 row_mask:0xf bank_mask:0xf
	v_mov_b32_dpp v86, v71 row_ror:1 row_mask:0xf bank_mask:0xf
	v_cndmask_b32_e64 v60, v80, v76, s[6:7]
	v_cndmask_b32_e64 v62, v77, v81, s[8:9]
	v_cndmask_b32_e64 v76, v89, v85, s[8:9]
	v_cndmask_b32_e64 v77, v91, v87, s[8:9]
	v_mov_b32_dpp v82, v69 row_ror:1 row_mask:0xf bank_mask:0xf
	v_cndmask_b32_e64 v63, v79, v83, s[8:9]
	v_cndmask_b32_e64 v74, v84, v88, s[6:7]
	v_cndmask_b32_e64 v75, v86, v90, s[6:7]
	v_pk_mul_f32 v[76:77], v[110:111], v[76:77]
	v_cndmask_b32_e64 v61, v82, v78, s[6:7]
	v_pk_mul_f32 v[62:63], v[108:109], v[62:63]
	v_pk_fma_f32 v[74:75], v[106:107], v[74:75], v[76:77]
	v_pk_fma_f32 v[60:61], v[104:105], v[60:61], v[62:63]
	v_pk_fma_f32 v[62:63], v[70:71], v[102:103], v[74:75]
	v_pk_fma_f32 v[60:61], v[68:69], v[100:101], v[60:61]
	v_pk_mul_f32 v[62:63], v[66:67], v[62:63]
	v_add_u32_e32 v66, s55, v183
	v_pk_mul_f32 v[60:61], v[72:73], v[60:61]
	v_cvt_pk_bf16_f32 v60, v60, v61
	v_cvt_pk_bf16_f32 v61, v62, v63
	v_lshlrev_b32_e32 v62, 11, v66
	v_add_u32_e32 v62, v62, v64
	global_store_dwordx2 v62, v[60:61], s[18:19]
	v_mov_b32_dpp v61, v128 row_ror:2 row_mask:0xf bank_mask:0xf
	v_mov_b32_dpp v63, v129 row_ror:1 row_mask:0xf bank_mask:0xf
	v_mov_b32_dpp v66, v129 row_ror:2 row_mask:0xf bank_mask:0xf
	v_mov_b32_dpp v60, v128 row_ror:1 row_mask:0xf bank_mask:0xf
	v_mov_b32_dpp v67, v130 row_ror:1 row_mask:0xf bank_mask:0xf
	v_mov_b32_dpp v68, v130 row_ror:2 row_mask:0xf bank_mask:0xf
	v_mov_b32_dpp v69, v131 row_ror:1 row_mask:0xf bank_mask:0xf
	v_mov_b32_dpp v70, v131 row_ror:2 row_mask:0xf bank_mask:0xf
	v_cndmask_b32_e64 v62, v81, v61, s[8:9]
	v_cndmask_b32_e64 v61, v63, v82, s[6:7]
	v_cndmask_b32_e64 v63, v83, v66, s[8:9]
	v_cndmask_b32_e64 v60, v60, v80, s[6:7]
	v_cndmask_b32_e64 v66, v67, v84, s[6:7]
	v_cndmask_b32_e64 v68, v85, v68, s[8:9]
	v_cndmask_b32_e64 v67, v69, v86, s[6:7]
	v_cndmask_b32_e64 v69, v87, v70, s[8:9]
	v_pk_mul_f32 v[62:63], v[108:109], v[62:63]
	v_pk_mul_f32 v[68:69], v[110:111], v[68:69]
	v_pk_fma_f32 v[60:61], v[104:105], v[60:61], v[62:63]
	v_pk_fma_f32 v[66:67], v[106:107], v[66:67], v[68:69]
	v_pk_fma_f32 v[60:61], v[128:129], v[100:101], v[60:61]
	v_pk_fma_f32 v[62:63], v[130:131], v[102:103], v[66:67]
	v_pk_mul_f32 v[56:57], v[56:57], v[60:61]
	v_add_u32_e32 v60, s55, v187
	v_pk_mul_f32 v[58:59], v[58:59], v[62:63]
	v_cvt_pk_bf16_f32 v56, v56, v57
	v_cvt_pk_bf16_f32 v57, v58, v59
	v_lshlrev_b32_e32 v58, 11, v60
	v_add_u32_e32 v58, v58, v64
	global_store_dwordx2 v58, v[56:57], s[18:19]
	v_mov_b32_e32 v60, 0
	s_andn2_b64 vcc, exec, s[48:49]
	v_mov_b32_e32 v61, 0
	v_mov_b32_e32 v62, 0
	v_mov_b32_e32 v63, 0
	v_mov_b32_e32 v56, 0
	v_mov_b32_e32 v57, 0
	v_mov_b32_e32 v58, 0
	v_mov_b32_e32 v59, 0
	s_cbranch_vccnz .LBB0_453
	ds_read_b128 v[60:63], v191
	ds_read_b128 v[56:59], v190
.LBB0_453:
	v_pk_mul_f32 v[40:41], v[40:41], v[176:177] op_sel_hi:[1,0]
	v_pk_mul_f32 v[42:43], v[42:43], v[176:177] op_sel_hi:[1,0]
	v_mul_f32_e32 v66, 0xbfb8aa3b, v40
	v_mul_f32_e32 v67, 0xbfb8aa3b, v41
	v_mul_f32_e32 v68, 0xbfb8aa3b, v42
	v_mul_f32_e32 v69, 0xbfb8aa3b, v43
	v_exp_f32_e32 v66, v66
	v_exp_f32_e32 v67, v67
	v_exp_f32_e32 v68, v68
	v_exp_f32_e32 v69, v69
	v_add_f32_e32 v66, 1.0, v66
	v_add_f32_e32 v67, 1.0, v67
	v_add_f32_e32 v68, 1.0, v68
	v_add_f32_e32 v69, 1.0, v69
	v_rcp_f32_e32 v66, v66
	v_rcp_f32_e32 v68, v68
	v_rcp_f32_e32 v69, v69
	v_rcp_f32_e32 v67, v67
	v_pk_mul_f32 v[50:51], v[50:51], v[176:177] op_sel_hi:[1,0]
	v_pk_mul_f32 v[48:49], v[48:49], v[176:177] op_sel_hi:[1,0]
	v_pk_mul_f32 v[46:47], v[46:47], v[176:177] op_sel_hi:[1,0]
	v_pk_mul_f32 v[44:45], v[44:45], v[176:177] op_sel_hi:[1,0]
	v_pk_mul_f32 v[54:55], v[54:55], v[176:177] op_sel_hi:[1,0]
	v_pk_mul_f32 v[52:53], v[52:53], v[176:177] op_sel_hi:[1,0]
	v_pk_mul_f32 v[70:71], v[50:51], v[46:47]
	v_pk_mul_f32 v[72:73], v[48:49], v[44:45]
	v_pk_mul_f32 v[42:43], v[42:43], v[68:69]
	v_pk_mul_f32 v[40:41], v[40:41], v[66:67]
	v_pk_mul_f32 v[42:43], v[54:55], v[42:43]
	v_pk_mul_f32 v[40:41], v[52:53], v[40:41]
	s_waitcnt lgkmcnt(0)
	v_cndmask_b32_e64 v53, v56, v60, s[6:7]
	v_cndmask_b32_e64 v55, v57, v61, s[6:7]
	v_cndmask_b32_e64 v60, v58, v62, s[6:7]
	v_cndmask_b32_e64 v61, v59, v63, s[6:7]
	v_mov_b32_dpp v44, v72 row_ror:1 row_mask:0xf bank_mask:0xf
	v_mov_b32_dpp v45, v72 row_ror:2 row_mask:0xf bank_mask:0xf
	v_mov_b32_dpp v46, v73 row_ror:1 row_mask:0xf bank_mask:0xf
	v_mov_b32_dpp v48, v70 row_ror:1 row_mask:0xf bank_mask:0xf
	v_mov_b32_dpp v49, v70 row_ror:2 row_mask:0xf bank_mask:0xf
	v_mov_b32_dpp v50, v71 row_ror:1 row_mask:0xf bank_mask:0xf
	v_mov_b32_dpp v51, v71 row_ror:2 row_mask:0xf bank_mask:0xf
	v_mov_b32_dpp v47, v73 row_ror:2 row_mask:0xf bank_mask:0xf
	v_cndmask_b32_e64 v52, v44, v56, s[6:7]
	v_cndmask_b32_e64 v54, v53, v45, s[8:9]
	v_cndmask_b32_e64 v53, v46, v57, s[6:7]
	v_cndmask_b32_e64 v56, v48, v58, s[6:7]
	v_cndmask_b32_e64 v58, v60, v49, s[8:9]
	v_cndmask_b32_e64 v57, v50, v59, s[6:7]
	v_cndmask_b32_e64 v59, v61, v51, s[8:9]
	v_cndmask_b32_e64 v55, v55, v47, s[8:9]
	v_pk_mul_f32 v[58:59], v[110:111], v[58:59]
	v_pk_mul_f32 v[54:55], v[108:109], v[54:55]
	v_pk_fma_f32 v[56:57], v[106:107], v[56:57], v[58:59]
	v_pk_fma_f32 v[52:53], v[104:105], v[52:53], v[54:55]
	v_pk_fma_f32 v[54:55], v[70:71], v[102:103], v[56:57]
	v_pk_fma_f32 v[52:53], v[72:73], v[100:101], v[52:53]
	v_pk_mul_f32 v[42:43], v[42:43], v[54:55]
	v_lshlrev_b32_e32 v54, 11, v170
	v_pk_mul_f32 v[40:41], v[40:41], v[52:53]
	v_lshl_add_u32 v54, v172, 1, v54
	v_cvt_pk_bf16_f32 v52, v40, v41
	v_cvt_pk_bf16_f32 v53, v42, v43
	global_store_dwordx2 v54, v[52:53], s[18:19]
	s_and_saveexec_b64 s[62:63], s[50:51]
	s_cbranch_execz .LBB0_455
	s_ashr_i32 s53, s52, 31
	s_lshl_b64 s[52:53], s[52:53], 13
	v_lshl_add_u64 v[52:53], v[146:147], 0, s[52:53]
	v_lshl_add_u64 v[52:53], v[52:53], 0, v[174:175]
	global_store_dwordx4 v[52:53], v[112:115], off
	v_lshl_add_u64 v[52:53], v[148:149], 0, s[52:53]
	v_lshl_add_u64 v[52:53], v[52:53], 0, v[174:175]
	global_store_dwordx4 v[52:53], v[40:43], off
.LBB0_455:
	s_or_b64 exec, exec, s[62:63]
	v_mov_b32_e32 v169, v168
	v_pk_mul_f32 v[32:33], v[32:33], v[168:169]
	v_mov_b32_e32 v41, v168
	v_mul_f32_e32 v40, 0xbfb8aa3b, v32
	v_mul_f32_e32 v43, 0xbfb8aa3b, v33
	v_exp_f32_e32 v42, v40
	v_exp_f32_e32 v43, v43
	v_mov_b32_e32 v40, v168
	v_pk_mul_f32 v[34:35], v[34:35], v[40:41]
	v_add_f32_e32 v42, 1.0, v42
	v_add_f32_e32 v43, 1.0, v43
	v_rcp_f32_e32 v42, v42
	v_rcp_f32_e32 v43, v43
	v_mul_f32_e32 v52, 0xbfb8aa3b, v34
	v_mul_f32_e32 v53, 0xbfb8aa3b, v35
	v_pk_mul_f32 v[36:37], v[36:37], v[168:169]
	v_pk_mul_f32 v[32:33], v[32:33], v[42:43]
	v_pk_mul_f32 v[20:21], v[20:21], v[166:167] op_sel_hi:[1,0]
	v_exp_f32_e32 v52, v52
	v_exp_f32_e32 v53, v53
	v_pk_mul_f32 v[38:39], v[38:39], v[40:41]
	v_mul_f32_e32 v40, 0xbfb8aa3b, v20
	v_pk_mul_f32 v[32:33], v[36:37], v[32:33]
	v_mul_f32_e32 v37, 0xbfb8aa3b, v21
	v_exp_f32_e32 v40, v40
	v_exp_f32_e32 v37, v37
	v_add_f32_e32 v52, 1.0, v52
	v_add_f32_e32 v53, 1.0, v53
	v_rcp_f32_e32 v52, v52
	v_rcp_f32_e32 v53, v53
	v_add_f32_e32 v36, 1.0, v40
	v_add_f32_e32 v37, 1.0, v37
	v_rcp_f32_e32 v36, v36
	v_rcp_f32_e32 v37, v37
	v_pk_mul_f32 v[34:35], v[34:35], v[52:53]
	v_pk_mul_f32 v[22:23], v[22:23], v[166:167] op_sel_hi:[1,0]
	v_pk_mul_f32 v[34:35], v[38:39], v[34:35]
	v_mul_f32_e32 v38, 0xbfb8aa3b, v22
	v_mul_f32_e32 v39, 0xbfb8aa3b, v23
	v_pk_mul_f32 v[28:29], v[28:29], v[166:167] op_sel_hi:[1,0]
	v_pk_mul_f32 v[20:21], v[20:21], v[36:37]
	v_pk_mul_f32 v[26:27], v[26:27], v[166:167] op_sel_hi:[1,0]
	v_pk_mul_f32 v[24:25], v[24:25], v[166:167] op_sel_hi:[1,0]
	v_pk_mul_f32 v[14:15], v[14:15], v[166:167] op_sel_hi:[1,0]
	v_pk_mul_f32 v[12:13], v[12:13], v[166:167] op_sel_hi:[1,0]
	v_pk_mul_f32 v[4:5], v[4:5], v[164:165] op_sel_hi:[1,0]
	v_pk_mul_f32 v[6:7], v[6:7], v[164:165] op_sel_hi:[1,0]
	v_exp_f32_e32 v38, v38
	v_exp_f32_e32 v39, v39
	v_pk_mul_f32 v[20:21], v[28:29], v[20:21]
	v_mul_f32_e32 v28, 0xbfb8aa3b, v4
	v_pk_mul_f32 v[14:15], v[26:27], v[14:15]
	v_pk_mul_f32 v[12:13], v[24:25], v[12:13]
	v_mul_f32_e32 v25, 0xbfb8aa3b, v5
	v_mul_f32_e32 v26, 0xbfb8aa3b, v6
	v_mul_f32_e32 v27, 0xbfb8aa3b, v7
	v_exp_f32_e32 v28, v28
	v_exp_f32_e32 v25, v25
	v_exp_f32_e32 v26, v26
	v_exp_f32_e32 v27, v27
	v_add_f32_e32 v38, 1.0, v38
	v_add_f32_e32 v39, 1.0, v39
	v_rcp_f32_e32 v38, v38
	v_rcp_f32_e32 v39, v39
	v_add_f32_e32 v24, 1.0, v28
	v_add_f32_e32 v25, 1.0, v25
	v_add_f32_e32 v26, 1.0, v26
	v_add_f32_e32 v27, 1.0, v27
	v_rcp_f32_e32 v24, v24
	v_rcp_f32_e32 v26, v26
	v_rcp_f32_e32 v27, v27
	v_rcp_f32_e32 v25, v25
	v_pk_mul_f32 v[30:31], v[30:31], v[166:167] op_sel_hi:[1,0]
	v_pk_mul_f32 v[22:23], v[22:23], v[38:39]
	v_pk_mul_f32 v[10:11], v[10:11], v[164:165] op_sel_hi:[1,0]
	v_pk_mul_f32 v[8:9], v[8:9], v[164:165] op_sel_hi:[1,0]
	v_pk_mul_f32 v[2:3], v[2:3], v[164:165] op_sel_hi:[1,0]
	v_pk_mul_f32 v[0:1], v[0:1], v[164:165] op_sel_hi:[1,0]
	v_pk_mul_f32 v[22:23], v[30:31], v[22:23]
	v_pk_mul_f32 v[6:7], v[6:7], v[26:27]
	v_pk_mul_f32 v[4:5], v[4:5], v[24:25]
	v_pk_mul_f32 v[2:3], v[10:11], v[2:3]
	v_pk_mul_f32 v[0:1], v[8:9], v[0:1]
	v_pk_mul_f32 v[18:19], v[18:19], v[164:165] op_sel_hi:[1,0]
	s_nop 0
	v_mov_b32_dpp v25, v0 row_ror:2 row_mask:0xf bank_mask:0xf
	v_mov_b32_dpp v27, v1 row_ror:2 row_mask:0xf bank_mask:0xf
	v_mov_b32_dpp v29, v2 row_ror:2 row_mask:0xf bank_mask:0xf
	v_mov_b32_dpp v31, v3 row_ror:2 row_mask:0xf bank_mask:0xf
	v_pk_mul_f32 v[16:17], v[16:17], v[164:165] op_sel_hi:[1,0]
	v_pk_mul_f32 v[6:7], v[18:19], v[6:7]
	v_mov_b32_dpp v24, v0 row_ror:1 row_mask:0xf bank_mask:0xf
	v_mov_b32_dpp v26, v1 row_ror:1 row_mask:0xf bank_mask:0xf
	v_mov_b32_dpp v28, v2 row_ror:1 row_mask:0xf bank_mask:0xf
	v_mov_b32_dpp v30, v3 row_ror:1 row_mask:0xf bank_mask:0xf
	v_cndmask_b32_e64 v10, v45, v25, s[8:9]
	v_cndmask_b32_e64 v11, v47, v27, s[8:9]
	v_cndmask_b32_e64 v18, v49, v29, s[8:9]
	v_cndmask_b32_e64 v19, v51, v31, s[8:9]
	v_pk_mul_f32 v[4:5], v[16:17], v[4:5]
	v_cndmask_b32_e64 v8, v24, v44, s[6:7]
	v_cndmask_b32_e64 v9, v26, v46, s[6:7]
	v_cndmask_b32_e64 v16, v28, v48, s[6:7]
	v_cndmask_b32_e64 v17, v30, v50, s[6:7]
	v_pk_mul_f32 v[18:19], v[110:111], v[18:19]
	v_pk_mul_f32 v[10:11], v[108:109], v[10:11]
	v_pk_fma_f32 v[16:17], v[106:107], v[16:17], v[18:19]
	v_pk_fma_f32 v[8:9], v[104:105], v[8:9], v[10:11]
	v_pk_fma_f32 v[2:3], v[2:3], v[102:103], v[16:17]
	v_pk_fma_f32 v[0:1], v[0:1], v[100:101], v[8:9]
	v_pk_mul_f32 v[2:3], v[6:7], v[2:3]
	v_pk_mul_f32 v[0:1], v[4:5], v[0:1]
	v_cvt_pk_bf16_f32 v0, v0, v1
	v_cvt_pk_bf16_f32 v1, v2, v3
	v_lshlrev_b32_e32 v2, 11, v162
	v_add_u32_e32 v2, v2, v64
	v_mov_b32_dpp v9, v12 row_ror:2 row_mask:0xf bank_mask:0xf
	v_mov_b32_dpp v11, v13 row_ror:2 row_mask:0xf bank_mask:0xf
	v_mov_b32_dpp v17, v14 row_ror:2 row_mask:0xf bank_mask:0xf
	v_mov_b32_dpp v19, v15 row_ror:2 row_mask:0xf bank_mask:0xf
	global_store_dwordx2 v2, v[0:1], s[18:19]
	v_mov_b32_dpp v8, v12 row_ror:1 row_mask:0xf bank_mask:0xf
	v_mov_b32_dpp v10, v13 row_ror:1 row_mask:0xf bank_mask:0xf
	v_mov_b32_dpp v16, v14 row_ror:1 row_mask:0xf bank_mask:0xf
	v_mov_b32_dpp v18, v15 row_ror:1 row_mask:0xf bank_mask:0xf
	v_cndmask_b32_e64 v2, v25, v9, s[8:9]
	v_cndmask_b32_e64 v3, v27, v11, s[8:9]
	v_cndmask_b32_e64 v6, v29, v17, s[8:9]
	v_cndmask_b32_e64 v7, v31, v19, s[8:9]
	v_cndmask_b32_e64 v0, v8, v24, s[6:7]
	v_cndmask_b32_e64 v1, v10, v26, s[6:7]
	v_cndmask_b32_e64 v4, v16, v28, s[6:7]
	v_cndmask_b32_e64 v5, v18, v30, s[6:7]
	v_pk_mul_f32 v[6:7], v[110:111], v[6:7]
	v_pk_mul_f32 v[2:3], v[108:109], v[2:3]
	v_pk_fma_f32 v[4:5], v[106:107], v[4:5], v[6:7]
	v_pk_fma_f32 v[0:1], v[104:105], v[0:1], v[2:3]
	v_pk_fma_f32 v[2:3], v[14:15], v[102:103], v[4:5]
	v_pk_fma_f32 v[0:1], v[12:13], v[100:101], v[0:1]
	v_pk_mul_f32 v[2:3], v[22:23], v[2:3]
	v_pk_mul_f32 v[0:1], v[20:21], v[0:1]
	v_cvt_pk_bf16_f32 v0, v0, v1
	v_cvt_pk_bf16_f32 v1, v2, v3
	v_lshlrev_b32_e32 v2, 11, v160
	v_add_u32_e32 v2, v2, v64
	global_store_dwordx2 v2, v[0:1], s[18:19]
	v_mov_b32_dpp v1, v92 row_ror:2 row_mask:0xf bank_mask:0xf
	v_mov_b32_dpp v3, v93 row_ror:1 row_mask:0xf bank_mask:0xf
	v_mov_b32_dpp v4, v93 row_ror:2 row_mask:0xf bank_mask:0xf
	v_mov_b32_dpp v5, v94 row_ror:1 row_mask:0xf bank_mask:0xf
	v_mov_b32_dpp v6, v94 row_ror:2 row_mask:0xf bank_mask:0xf
	v_mov_b32_dpp v7, v95 row_ror:1 row_mask:0xf bank_mask:0xf
	v_mov_b32_dpp v12, v95 row_ror:2 row_mask:0xf bank_mask:0xf
	v_mov_b32_dpp v0, v92 row_ror:1 row_mask:0xf bank_mask:0xf
	v_cndmask_b32_e64 v2, v9, v1, s[8:9]
	v_cndmask_b32_e64 v1, v3, v10, s[6:7]
	v_cndmask_b32_e64 v3, v11, v4, s[8:9]
	v_cndmask_b32_e64 v4, v5, v16, s[6:7]
	v_cndmask_b32_e64 v6, v17, v6, s[8:9]
	v_cndmask_b32_e64 v5, v7, v18, s[6:7]
	v_cndmask_b32_e64 v7, v19, v12, s[8:9]
	v_cndmask_b32_e64 v0, v0, v8, s[6:7]
	v_pk_mul_f32 v[6:7], v[110:111], v[6:7]
	v_pk_mul_f32 v[2:3], v[108:109], v[2:3]
	v_pk_fma_f32 v[4:5], v[106:107], v[4:5], v[6:7]
	v_pk_fma_f32 v[0:1], v[104:105], v[0:1], v[2:3]
	v_pk_fma_f32 v[2:3], v[94:95], v[102:103], v[4:5]
	v_pk_fma_f32 v[0:1], v[92:93], v[100:101], v[0:1]
	v_pk_mul_f32 v[2:3], v[34:35], v[2:3]
	v_pk_mul_f32 v[0:1], v[32:33], v[0:1]
	s_andn2_b64 vcc, exec, s[10:11]
	v_cvt_pk_bf16_f32 v0, v0, v1
	v_cvt_pk_bf16_f32 v1, v2, v3
	v_lshlrev_b32_e32 v2, 11, v158
	v_add_u32_e32 v2, v2, v64
	global_store_dwordx2 v2, v[0:1], s[18:19]
	s_waitcnt lgkmcnt(0)
	s_mov_b64 s[10:11], -1
	s_cbranch_vccnz .LBB0_431
	s_andn2_b64 vcc, exec, s[16:17]
	s_cbranch_vccnz .LBB0_430
	s_barrier
	s_branch .LBB0_430
